# sample-attention loop: the 32 value loads use a scalar row base plus one per-lane offset register (no per-load 64-bit vector address add)
# baseline (speedup 1.0000x reference)
; __device__ __forceinline__ void sattn_unit(const Args& a, LAS unsigned char* lds, const LAS float* bt, int db, int h, int t, int tid, int wave, int lane) {
;     ...
;         if (it + 1 < nf) SA_LOAD(key0 + 32);
.LBB0_295:
	ds_write_b128 v172, v[64:67] offset:40960
	ds_write_b128 v172, v[68:71] offset:42048
	ds_write_b128 v172, v[72:75] offset:43136
	ds_write_b128 v172, v[76:79] offset:44224
	ds_write_b128 v172, v[80:83] offset:45312
	ds_write_b128 v172, v[84:87] offset:46400
	ds_write_b128 v172, v[88:91] offset:47488
	ds_write_b128 v172, v[92:95] offset:48576
	ds_read_b128 v[108:111], v170 offset:40960
	ds_read_b128 v[104:107], v170 offset:40976
	ds_read_b128 v[100:103], v170 offset:41024
	ds_read_b128 v[96:99], v170 offset:41040
	ds_read_b128 v[44:47], v170 offset:41088
	ds_read_b128 v[40:43], v170 offset:41104
	ds_read_b128 v[36:39], v170 offset:41152
	ds_read_b128 v[32:35], v170 offset:41168
	s_add_i32 s0, s96, s35
	s_lshl_b32 vcc_lo, s0, 5
	s_add_i32 s35, s35, 1
	s_cmp_ge_u32 s35, s97
	s_cbranch_scc1 .LBB0_297
	s_add_i32 s0, s30, vcc_lo
	s_ashr_i32 s1, s0, 31
	s_lshl_b64 s[0:1], s[0:1], 12
	s_lshl_b32 s14, s5, 2
	s_or_b32 s0, s0, s14
	s_add_u32 s48, s93, s0
	s_addc_u32 s49, s89, s1
	s_add_u32 s0, s42, s0
	s_addc_u32 s1, s43, s1
	v_lshl_add_u64 v[64:65], v[112:113], 2, s[48:49]
	v_lshl_add_u64 v[68:69], v[120:121], 2, s[48:49]
	v_lshl_add_u64 v[72:73], v[122:123], 2, s[48:49]
	v_lshl_add_u64 v[76:77], v[124:125], 2, s[48:49]
	v_lshl_add_u64 v[80:81], v[126:127], 2, s[48:49]
	v_lshl_add_u64 v[84:85], v[128:129], 2, s[48:49]
	v_lshl_add_u64 v[88:89], v[130:131], 2, s[48:49]
	v_lshl_add_u64 v[92:93], v[132:133], 2, s[48:49]
	global_load_dwordx4 v[64:67], v[64:65], off
	s_nop 0
	global_load_dwordx4 v[68:71], v[68:69], off
	s_nop 0
	global_load_dwordx4 v[72:75], v[72:73], off
	s_nop 0
	global_load_dwordx4 v[76:79], v[76:77], off
	s_nop 0
	global_load_dwordx4 v[80:83], v[80:81], off
	s_nop 0
	global_load_dwordx4 v[84:87], v[84:85], off
	s_nop 0
	global_load_dwordx4 v[88:91], v[88:89], off
	s_nop 0
	global_load_dwordx4 v[92:95], v[92:93], off
	s_nop 0
	global_load_dword v176, v134, s[0:1]
	global_load_dword v174, v134, s[0:1] offset:128
	s_add_u32 s14, s0, 0x10000
	s_addc_u32 s15, s1, 0
	global_load_dword v175, v134, s[14:15]
	global_load_dword v173, v136, s[14:15]
	s_add_u32 s48, s0, 0x1000
	s_addc_u32 s49, s1, 0
	global_load_dword v179, v134, s[48:49]
	global_load_dword v177, v136, s[48:49]
	s_add_u32 s14, s0, 0x11000
	s_addc_u32 s15, s1, 0
	global_load_dword v178, v134, s[14:15]
	global_load_dword v180, v136, s[14:15]
	s_add_u32 s48, s0, 0x2000
	s_addc_u32 s49, s1, 0
	global_load_dword v195, v134, s[48:49]
	global_load_dword v184, v136, s[48:49]
	s_add_u32 s14, s0, 0x12000
	s_addc_u32 s15, s1, 0
	global_load_dword v186, v134, s[14:15]
	global_load_dword v183, v136, s[14:15]
	s_add_u32 s48, s0, 0x3000
	s_addc_u32 s49, s1, 0
	global_load_dword v204, v134, s[48:49]
	global_load_dword v200, v136, s[48:49]
	s_add_u32 s14, s0, 0x13000
	s_addc_u32 s15, s1, 0
	global_load_dword v202, v134, s[14:15]
	global_load_dword v207, v136, s[14:15]
	s_add_u32 s48, s0, 0x8000
	s_addc_u32 s49, s1, 0
	global_load_dword v219, v134, s[48:49]
	global_load_dword v216, v136, s[48:49]
	s_add_u32 s14, s0, 0x18000
	s_addc_u32 s15, s1, 0
	global_load_dword v218, v134, s[14:15]
	global_load_dword v214, v136, s[14:15]
	s_add_u32 s48, s0, 0x9000
	s_addc_u32 s49, s1, 0
	global_load_dword v228, v134, s[48:49]
	global_load_dword v224, v136, s[48:49]
	s_add_u32 s14, s0, 0x19000
	s_addc_u32 s15, s1, 0
	global_load_dword v226, v134, s[14:15]
	global_load_dword v231, v136, s[14:15]
	s_add_u32 s48, s0, 0xa000
	s_addc_u32 s49, s1, 0
	global_load_dword v239, v134, s[48:49]
	global_load_dword v237, v136, s[48:49]
	s_add_u32 s14, s0, 0x1a000
	s_addc_u32 s15, s1, 0
	global_load_dword v238, v134, s[14:15]
	global_load_dword v236, v136, s[14:15]
	s_add_u32 s48, s0, 0xb000
	s_addc_u32 s49, s1, 0
	global_load_dword v242, v134, s[48:49]
	global_load_dword v240, v136, s[48:49]
	s_add_u32 s14, s0, 0x1b000
	s_addc_u32 s15, s1, 0
	global_load_dword v241, v134, s[14:15]
	global_load_dword v243, v136, s[14:15]
